# attention: three tile-loop variants (unmasked / before-block / after-block), no integer multiply in the window mask, V fragment reads hoisted
# speedup vs baseline: 1.0013x; 1.0013x over previous
; #define LAS __attribute__((address_space(3)))
; __device__ __forceinline__ void attn_phase(LAS unsigned char* lds, bf16* qkv, const float* qgain, const float* kgain, const float* sink, const float* ropetab, int G, int bid) {
;     ...
;             const int msg = (type == 0) ? 1 : (type == 2 ? -1 : 0);
; #pragma unroll 1
;             for (int T = 0; T < 4; ++T) {
;                 bf16x8 kf[2][2];
; #pragma unroll
;                 for (int sub = 0; sub < 2; ++sub)
; #pragma unroll
;                     for (int dh = 0; dh < 2; ++dh) kf[sub][dh] = *(const LAS bf16x8*)(Ks + (T * 32 + sub * 16 + fr) * 160 + dh * 64 + fq * 16);
;                 bf16x8 pb[4];
; #pragma unroll
;                 for (int qi = 0; qi < 4; ++qi) {
;                     f32x4 s0 = (f32x4){0.f, 0.f, 0.f, 0.f}, s1 = (f32x4){0.f, 0.f, 0.f, 0.f};
;                     s0 = __builtin_amdgcn_mfma_f32_16x16x32_bf16(kf[0][0], qf[qi][0], s0, 0, 0, 0);
;                     s0 = __builtin_amdgcn_mfma_f32_16x16x32_bf16(kf[0][1], qf[qi][1], s0, 0, 0, 0);
;                     s1 = __builtin_amdgcn_mfma_f32_16x16x32_bf16(kf[1][0], qf[qi][0], s1, 0, 0, 0);
;                     s1 = __builtin_amdgcn_mfma_f32_16x16x32_bf16(kf[1][1], qf[qi][1], s1, 0, 0, 0);
;                     const int mbase = msg * (T * 32 + fq * 4 - (whalf * 64 + qi * 16 + fr));
;                     float p0[4], p1[4];
; #pragma unroll
;                     for (int j = 0; j < 4; ++j) {
;                         const float e0 = __builtin_amdgcn_exp2f(s0[j] - Mshift), e1 = __builtin_amdgcn_exp2f(s1[j] - Mshift);
;                         p0[j] = (mbase + msg * j >= 0) ? e0 : 0.f;
;                         p1[j] = (mbase + msg * (16 + j) >= 0) ? e1 : 0.f;
;                     }
;                     lsum[qi] += (p0[0] + p0[1]) + (p0[2] + p0[3]) + (p1[0] + p1[1]) + (p1[2] + p1[3]);
;                     u32x4 w; w.x = cvt_pk_bf16(p0[0], p0[1]); w.y = cvt_pk_bf16(p0[2], p0[3]); w.z = cvt_pk_bf16(p1[0], p1[1]); w.w = cvt_pk_bf16(p1[2], p1[3]);
;                     pb[qi] = __builtin_bit_cast(bf16x8, w);
;                 }
.LBB0_586:
	s_xor_b64 s[36:37], s[4:5], -1
	s_cmp_eq_u32 s18, 2
	s_waitcnt lgkmcnt(0)
	s_barrier
	s_cselect_b64 s[0:1], -1, 0
	s_cmp_lg_u32 s18, 0
	v_cndmask_b32_e64 v3, 0, -1, s[0:1]
	s_cselect_b64 vcc, -1, 0
	s_mov_b32 s4, 0
	v_cndmask_b32_e32 v3, 1, v3, vcc
	v_mov_b32_e32 v151, v185
	v_mov_b32_e32 v153, v187
	s_cmp_eq_u32 s18, 2
	s_cbranch_scc1 .LattN_587
	s_cmp_lg_u32 s18, 0
	s_cbranch_scc1 .LattU_587
.LBB0_587:
	ds_read_b128 v[124:127], v153
	ds_read_b128 v[128:131], v153 offset:64
	ds_read_b128 v[132:135], v153 offset:2560
	ds_read_b128 v[136:139], v153 offset:2624
	v_add_u32_e32 v240, s4, v186
	ds_read2_b64 v[224:227], v240 offset1:4
	v_add_u32_e32 v241, 0x1000, v240
	ds_read2_b64 v[228:231], v241 offset0:32 offset1:36
	v_add_u32_e32 v241, 0x2000, v240
	ds_read2_b64 v[232:235], v241 offset0:64 offset1:68
	v_add_u32_e32 v241, 0x3000, v240
	ds_read2_b64 v[236:239], v241 offset0:96 offset1:100
	v_add_u32_e32 v205, v151, v141
	s_waitcnt lgkmcnt(7)
	v_mfma_f32_16x16x32_bf16 v[116:119], v[124:127], v[108:111], 0
	v_add_u32_e32 v206, v151, v140
	v_mov_b32_e32 v201, v205
	v_mov_b32_e32 v197, v206
	s_waitcnt lgkmcnt(5)
	v_mfma_f32_16x16x32_bf16 v[120:123], v[132:135], v[108:111], 0
	v_cmp_lt_i32_e64 s[40:41], -1, v201
	v_cmp_lt_i32_e64 s[0:1], -1, v197
	v_add_u32_e32 v153, 0x1400, v153
	v_mfma_f32_16x16x32_bf16 v[116:119], v[128:131], v[112:115], v[116:119]
	s_waitcnt lgkmcnt(4)
	v_mfma_f32_16x16x32_bf16 v[120:123], v[136:139], v[112:115], v[120:123]
	s_nop 5
	v_sub_f32_e32 v116, v116, v174
	v_exp_f32_e32 v191, v116
	v_sub_f32_e32 v116, v120, v174
	v_exp_f32_e32 v192, v116
	v_sub_f32_e32 v116, v117, v174
	v_exp_f32_e32 v194, v116
	v_sub_f32_e32 v116, v121, v174
	v_exp_f32_e32 v196, v116
	v_sub_f32_e32 v116, v118, v174
	v_exp_f32_e32 v198, v116
	v_sub_f32_e32 v116, v122, v174
	v_exp_f32_e32 v200, v116
	v_sub_f32_e32 v116, v119, v174
	v_exp_f32_e32 v202, v116
	v_sub_f32_e32 v116, v123, v174
	v_exp_f32_e32 v204, v116
	v_mfma_f32_16x16x32_bf16 v[116:119], v[124:127], v[68:71], 0
	v_mfma_f32_16x16x32_bf16 v[120:123], v[132:135], v[68:71], 0
	v_mfma_f32_16x16x32_bf16 v[116:119], v[128:131], v[100:103], v[116:119]
	v_mfma_f32_16x16x32_bf16 v[120:123], v[136:139], v[100:103], v[120:123]
	s_nop 6
	v_sub_f32_e32 v116, v116, v174
	v_sub_f32_e32 v120, v120, v174
	v_exp_f32_e32 v116, v116
	v_exp_f32_e32 v193, v120
	v_sub_f32_e32 v120, v121, v174
	v_sub_f32_e32 v117, v117, v174
	v_exp_f32_e32 v195, v120
	v_sub_f32_e32 v120, v122, v174
	v_exp_f32_e32 v117, v117
	v_exp_f32_e32 v199, v120
	v_sub_f32_e32 v120, v123, v174
	v_exp_f32_e32 v203, v120
	v_add_u32_e32 v120, 16, v206
	v_mov_b32_e32 v120, v120
	v_cndmask_b32_e64 v121, 0, v116, s[40:41]
	v_add_u32_e32 v116, 1, v201
	v_cmp_lt_i32_e32 vcc, -1, v120
	v_cndmask_b32_e64 v120, 0, v191, s[0:1]
	v_cndmask_b32_e64 v123, 0, v193, s[0:1]
	v_cmp_lt_i32_e64 s[0:1], -1, v116
	v_add_u32_e32 v191, 1, v197
	v_add_u32_e32 v116, 17, v206
	v_cndmask_b32_e64 v193, 0, v117, s[0:1]
	v_add_u32_e32 v117, 17, v205
	v_sub_f32_e32 v118, v118, v174
	v_cndmask_b32_e32 v122, 0, v192, vcc
	v_cmp_lt_i32_e32 vcc, -1, v191
	v_mov_b32_e32 v117, v117
	v_mov_b32_e32 v116, v116
	v_exp_f32_e32 v118, v118
	v_cndmask_b32_e32 v192, 0, v194, vcc
	v_cmp_lt_i32_e32 vcc, -1, v116
	v_cmp_lt_i32_e64 s[0:1], -1, v117
	v_add_u32_e32 v116, 2, v206
	v_add_u32_e32 v117, 2, v205
	v_mov_b32_e32 v117, v117
	v_mov_b32_e32 v116, v116
	v_sub_f32_e32 v119, v119, v174
	v_cndmask_b32_e64 v195, 0, v195, s[0:1]
	v_cndmask_b32_e32 v194, 0, v196, vcc
	v_cmp_lt_i32_e32 vcc, -1, v116
	v_cmp_lt_i32_e64 s[0:1], -1, v117
	v_add_u32_e32 v116, 18, v206
	v_add_u32_e32 v117, 18, v205
	v_exp_f32_e32 v119, v119
	v_mov_b32_e32 v117, v117
	v_mov_b32_e32 v116, v116
	v_cndmask_b32_e64 v197, 0, v118, s[0:1]
	v_cndmask_b32_e32 v196, 0, v198, vcc
	v_cmp_lt_i32_e32 vcc, -1, v116
	v_cmp_lt_i32_e64 s[0:1], -1, v117
	v_add_u32_e32 v116, 3, v206
	v_add_u32_e32 v117, 3, v205
	v_mov_b32_e32 v117, v117
	v_mov_b32_e32 v116, v116
	v_cndmask_b32_e64 v199, 0, v199, s[0:1]
	v_cndmask_b32_e32 v198, 0, v200, vcc
	v_cmp_lt_i32_e32 vcc, -1, v116
	v_cmp_lt_i32_e64 s[0:1], -1, v117
	v_add_u32_e32 v116, 19, v206
	v_add_u32_e32 v117, 19, v205
	v_cndmask_b32_e64 v201, 0, v119, s[0:1]
	v_cndmask_b32_e32 v200, 0, v202, vcc
	v_mov_b32_e32 v117, v117
	v_mov_b32_e32 v116, v116
	v_cmp_lt_i32_e32 vcc, -1, v116
	v_cmp_lt_i32_e64 s[0:1], -1, v117
	v_pk_add_f32 v[116:117], v[120:121], v[192:193]
	v_pk_add_f32 v[118:119], v[196:197], v[200:201]
	v_cndmask_b32_e64 v203, 0, v203, s[0:1]
	v_cndmask_b32_e32 v202, 0, v204, vcc
	v_pk_add_f32 v[116:117], v[116:117], v[118:119]
	v_pk_add_f32 v[118:119], v[122:123], v[194:195]
	s_nop 0
	v_pk_add_f32 v[116:117], v[116:117], v[118:119]
	v_pk_add_f32 v[118:119], v[198:199], v[202:203]
	s_nop 0
	v_pk_add_f32 v[204:205], v[118:119], v[116:117]
	v_cvt_pk_bf16_f32 v116, v120, v192
	v_cvt_pk_bf16_f32 v118, v122, v194
	v_cvt_pk_bf16_f32 v120, v121, v193
	v_cvt_pk_bf16_f32 v122, v123, v195
	v_mfma_f32_16x16x32_bf16 v[192:195], v[124:127], v[60:63], 0
	v_cvt_pk_bf16_f32 v117, v196, v200
	v_cvt_pk_bf16_f32 v119, v198, v202
	v_cvt_pk_bf16_f32 v121, v197, v201
	v_mfma_f32_16x16x32_bf16 v[124:127], v[124:127], v[52:55], 0
	v_cvt_pk_bf16_f32 v123, v199, v203
	v_pk_add_f32 v[170:171], v[170:171], v[204:205]
	v_mfma_f32_16x16x32_bf16 v[198:201], v[128:131], v[64:67], v[192:195]
	v_mfma_f32_16x16x32_bf16 v[128:131], v[128:131], v[56:59], v[124:127]
	v_mfma_f32_16x16x32_bf16 v[124:127], v[132:135], v[52:55], 0
	s_nop 5
	v_sub_f32_e32 v191, v198, v174
	v_exp_f32_e32 v198, v191
	v_mfma_f32_16x16x32_bf16 v[192:195], v[132:135], v[60:63], 0
	v_mfma_f32_16x16x32_bf16 v[132:135], v[136:139], v[56:59], v[124:127]
; #define LAS __attribute__((address_space(3)))
; __device__ __forceinline__ void attn_phase(LAS unsigned char* lds, bf16* qkv, const float* qgain, const float* kgain, const float* sink, const float* ropetab, int G, int bid) {
;     ...
;                     const int mbase = msg * (T * 32 + fq * 4 - (whalf * 64 + qi * 16 + fr));
;                     float p0[4], p1[4];
; #pragma unroll
;                     for (int j = 0; j < 4; ++j) {
;                         const float e0 = __builtin_amdgcn_exp2f(s0[j] - Mshift), e1 = __builtin_amdgcn_exp2f(s1[j] - Mshift);
;                         p0[j] = (mbase + msg * j >= 0) ? e0 : 0.f;
;                         p1[j] = (mbase + msg * (16 + j) >= 0) ? e1 : 0.f;
;                     }
;                     lsum[qi] += (p0[0] + p0[1]) + (p0[2] + p0[3]) + (p1[0] + p1[1]) + (p1[2] + p1[3]);
;                     u32x4 w; w.x = cvt_pk_bf16(p0[0], p0[1]); w.y = cvt_pk_bf16(p0[2], p0[3]); w.z = cvt_pk_bf16(p1[0], p1[1]); w.w = cvt_pk_bf16(p1[2], p1[3]);
;                     pb[qi] = __builtin_bit_cast(bf16x8, w);
;                 }
; #pragma unroll
;                 for (int dt = 0; dt < 4; ++dt) {
;                     const LAS unsigned char* vp = Vt + (dt * 16 + fr) * 272 + (T * 32 + fq * 4) * 2;
;                     const u32x2 lo = *(const LAS u32x2*)vp, hi = *(const LAS u32x2*)(vp + 32);
;                     u32x4 w; w.x = lo[0]; w.y = lo[1]; w.z = hi[0]; w.w = hi[1];
;                     const bf16x8 vf = __builtin_bit_cast(bf16x8, w);
; #pragma unroll
;                     for (int qi = 0; qi < 4; ++qi) o[dt][qi] = __builtin_amdgcn_mfma_f32_16x16x32_bf16(vf, pb[qi], o[dt][qi], 0, 0, 0);
;                 }
	v_mfma_f32_16x16x32_bf16 v[202:205], v[136:139], v[64:67], v[192:195]
	s_nop 1
	v_sub_f32_e32 v124, v128, v174
	v_exp_f32_e32 v136, v124
	s_nop 2
	v_sub_f32_e32 v124, v132, v174
	v_exp_f32_e32 v132, v124
	v_sub_f32_e32 v124, v129, v174
	v_exp_f32_e32 v129, v124
	v_sub_f32_e32 v124, v133, v174
	v_sub_f32_e32 v191, v202, v174
	v_exp_f32_e32 v128, v124
	v_sub_f32_e32 v124, v130, v174
	v_exp_f32_e32 v197, v191
	v_sub_f32_e32 v191, v199, v174
	v_exp_f32_e32 v127, v124
	v_sub_f32_e32 v124, v134, v174
	v_exp_f32_e32 v196, v191
	v_sub_f32_e32 v191, v203, v174
	v_exp_f32_e32 v126, v124
	v_sub_f32_e32 v124, v131, v174
	v_add_u32_e32 v199, v147, v151
	v_exp_f32_e32 v195, v191
	v_sub_f32_e32 v191, v200, v174
	v_exp_f32_e32 v125, v124
	v_sub_f32_e32 v124, v135, v174
	v_add_u32_e32 v200, v146, v151
	v_add_u32_e32 v134, 16, v199
	v_mov_b32_e32 v135, v199
	v_add_u32_e32 v133, 16, v200
	v_mov_b32_e32 v137, v200
	v_cmp_lt_i32_e64 s[0:1], -1, v135
	v_mov_b32_e32 v134, v134
	v_cmp_lt_i32_e32 vcc, -1, v137
	v_cndmask_b32_e64 v131, 0, v136, s[0:1]
	v_mov_b32_e32 v133, v133
	v_cmp_lt_i32_e64 s[0:1], -1, v134
	v_add_u32_e32 v134, 1, v135
	v_cndmask_b32_e32 v130, 0, v198, vcc
	v_cmp_lt_i32_e32 vcc, -1, v133
	v_cndmask_b32_e64 v133, 0, v132, s[0:1]
	v_add_u32_e32 v135, 1, v137
	v_cmp_lt_i32_e64 s[0:1], -1, v134
	v_cndmask_b32_e32 v132, 0, v197, vcc
	v_cmp_lt_i32_e32 vcc, -1, v135
	v_cndmask_b32_e64 v135, 0, v129, s[0:1]
	v_add_u32_e32 v129, 17, v200
	v_add_u32_e32 v136, 17, v199
	v_mov_b32_e32 v129, v129
	v_cndmask_b32_e32 v134, 0, v196, vcc
	v_mov_b32_e32 v136, v136
	v_cmp_lt_i32_e32 vcc, -1, v129
	v_add_u32_e32 v129, 2, v199
	v_exp_f32_e32 v194, v191
	v_cmp_lt_i32_e64 s[0:1], -1, v136
	v_mov_b32_e32 v129, v129
	v_sub_f32_e32 v191, v204, v174
	v_cndmask_b32_e64 v137, 0, v128, s[0:1]
	v_add_u32_e32 v128, 2, v200
	v_cmp_lt_i32_e64 s[0:1], -1, v129
	v_add_u32_e32 v138, 18, v199
	v_exp_f32_e32 v193, v191
	v_mov_b32_e32 v128, v128
	v_cndmask_b32_e64 v129, 0, v127, s[0:1]
	v_add_u32_e32 v127, 18, v200
	v_mov_b32_e32 v138, v138
	v_sub_f32_e32 v191, v201, v174
	v_cndmask_b32_e32 v136, 0, v195, vcc
	v_cmp_lt_i32_e32 vcc, -1, v128
	v_mov_b32_e32 v127, v127
	v_cmp_lt_i32_e64 s[0:1], -1, v138
	v_exp_f32_e32 v192, v191
	v_cndmask_b32_e32 v128, 0, v194, vcc
	v_cmp_lt_i32_e32 vcc, -1, v127
	v_cndmask_b32_e64 v139, 0, v126, s[0:1]
	v_add_u32_e32 v126, 3, v200
	v_add_u32_e32 v127, 3, v199
	v_sub_f32_e32 v191, v205, v174
	v_exp_f32_e32 v124, v124
	v_mov_b32_e32 v127, v127
	v_mov_b32_e32 v126, v126
	v_exp_f32_e32 v191, v191
	v_cndmask_b32_e32 v138, 0, v193, vcc
	v_cmp_lt_i32_e32 vcc, -1, v126
	v_cmp_lt_i32_e64 s[0:1], -1, v127
	v_add_u32_e32 v126, 19, v199
	v_mov_b32_e32 v126, v126
	v_cndmask_b32_e64 v193, 0, v125, s[0:1]
	v_add_u32_e32 v125, 19, v200
	v_cndmask_b32_e32 v192, 0, v192, vcc
	v_mov_b32_e32 v125, v125
	v_cmp_lt_i32_e64 s[0:1], -1, v126
	v_cmp_lt_i32_e32 vcc, -1, v125
	v_pk_add_f32 v[126:127], v[128:129], v[192:193]
	v_cndmask_b32_e64 v195, 0, v124, s[0:1]
	v_pk_add_f32 v[124:125], v[130:131], v[134:135]
	v_cndmask_b32_e32 v194, 0, v191, vcc
	v_pk_add_f32 v[124:125], v[124:125], v[126:127]
	v_pk_add_f32 v[126:127], v[132:133], v[136:137]
	v_cvt_pk_bf16_f32 v129, v129, v193
	v_pk_add_f32 v[124:125], v[124:125], v[126:127]
	v_pk_add_f32 v[126:127], v[138:139], v[194:195]
	v_add_u32_e32 v151, 32, v151
	v_pk_add_f32 v[196:197], v[126:127], v[124:125]
	v_cvt_pk_bf16_f32 v126, v132, v136
	v_cvt_pk_bf16_f32 v124, v130, v134
	v_cvt_pk_bf16_f32 v125, v128, v192
	v_cvt_pk_bf16_f32 v128, v131, v135
	v_cvt_pk_bf16_f32 v130, v133, v137
	v_cvt_pk_bf16_f32 v127, v138, v194
	v_cvt_pk_bf16_f32 v131, v139, v195
	s_waitcnt lgkmcnt(0)
	v_mfma_f32_16x16x32_bf16 v[104:107], v[224:227], v[116:119], v[104:107]
	s_add_i32 s4, s4, 64
	v_pk_add_f32 v[160:161], v[160:161], v[196:197]
	s_cmpk_eq_i32 s4, 0x100
	v_mfma_f32_16x16x32_bf16 v[48:51], v[224:227], v[120:123], v[48:51]
	v_mfma_f32_16x16x32_bf16 v[32:35], v[224:227], v[124:127], v[32:35]
	v_mfma_f32_16x16x32_bf16 v[16:19], v[224:227], v[128:131], v[16:19]
	v_mfma_f32_16x16x32_bf16 v[96:99], v[228:231], v[116:119], v[96:99]
	v_mfma_f32_16x16x32_bf16 v[40:43], v[228:231], v[120:123], v[40:43]
	v_mfma_f32_16x16x32_bf16 v[24:27], v[228:231], v[124:127], v[24:27]
	v_mfma_f32_16x16x32_bf16 v[4:7], v[228:231], v[128:131], v[4:7]
	v_mfma_f32_16x16x32_bf16 v[88:91], v[232:235], v[116:119], v[88:91]
	v_mfma_f32_16x16x32_bf16 v[44:47], v[232:235], v[120:123], v[44:47]
	v_mfma_f32_16x16x32_bf16 v[28:31], v[232:235], v[124:127], v[28:31]
	v_mfma_f32_16x16x32_bf16 v[12:15], v[232:235], v[128:131], v[12:15]
	v_mfma_f32_16x16x32_bf16 v[80:83], v[236:239], v[116:119], v[80:83]
	v_mfma_f32_16x16x32_bf16 v[36:39], v[236:239], v[120:123], v[36:39]
	v_mfma_f32_16x16x32_bf16 v[20:23], v[236:239], v[124:127], v[20:23]
	v_mfma_f32_16x16x32_bf16 v[8:11], v[236:239], v[128:131], v[8:11]
	s_cbranch_scc0 .LBB0_587
	s_branch .Latt_exit
; #define LAS __attribute__((address_space(3)))
; __device__ __forceinline__ void attn_phase(LAS unsigned char* lds, bf16* qkv, const float* qgain, const float* kgain, const float* sink, const float* ropetab, int G, int bid) {
;     ...
;             for (int T = 0; T < 4; ++T) {
;                 bf16x8 kf[2][2];
; #pragma unroll
;                 for (int sub = 0; sub < 2; ++sub)
; #pragma unroll
;                     for (int dh = 0; dh < 2; ++dh) kf[sub][dh] = *(const LAS bf16x8*)(Ks + (T * 32 + sub * 16 + fr) * 160 + dh * 64 + fq * 16);
;                 bf16x8 pb[4];
; #pragma unroll
;                 for (int qi = 0; qi < 4; ++qi) {
;                     f32x4 s0 = (f32x4){0.f, 0.f, 0.f, 0.f}, s1 = (f32x4){0.f, 0.f, 0.f, 0.f};
;                     s0 = __builtin_amdgcn_mfma_f32_16x16x32_bf16(kf[0][0], qf[qi][0], s0, 0, 0, 0);
;                     s0 = __builtin_amdgcn_mfma_f32_16x16x32_bf16(kf[0][1], qf[qi][1], s0, 0, 0, 0);
;                     s1 = __builtin_amdgcn_mfma_f32_16x16x32_bf16(kf[1][0], qf[qi][0], s1, 0, 0, 0);
;                     s1 = __builtin_amdgcn_mfma_f32_16x16x32_bf16(kf[1][1], qf[qi][1], s1, 0, 0, 0);
;                     const int mbase = msg * (T * 32 + fq * 4 - (whalf * 64 + qi * 16 + fr));
;                     float p0[4], p1[4];
; #pragma unroll
;                     for (int j = 0; j < 4; ++j) {
;                         const float e0 = __builtin_amdgcn_exp2f(s0[j] - Mshift), e1 = __builtin_amdgcn_exp2f(s1[j] - Mshift);
;                         p0[j] = (mbase + msg * j >= 0) ? e0 : 0.f;
;                         p1[j] = (mbase + msg * (16 + j) >= 0) ? e1 : 0.f;
;                     }
;                     lsum[qi] += (p0[0] + p0[1]) + (p0[2] + p0[3]) + (p1[0] + p1[1]) + (p1[2] + p1[3]);
;                     u32x4 w; w.x = cvt_pk_bf16(p0[0], p0[1]); w.y = cvt_pk_bf16(p0[2], p0[3]); w.z = cvt_pk_bf16(p1[0], p1[1]); w.w = cvt_pk_bf16(p1[2], p1[3]);
;                     pb[qi] = __builtin_bit_cast(bf16x8, w);
;                 }
.LattN_587:
	ds_read_b128 v[124:127], v153
	ds_read_b128 v[128:131], v153 offset:64
	ds_read_b128 v[132:135], v153 offset:2560
	ds_read_b128 v[136:139], v153 offset:2624
	v_add_u32_e32 v240, s4, v186
	ds_read2_b64 v[224:227], v240 offset1:4
	v_add_u32_e32 v241, 0x1000, v240
	ds_read2_b64 v[228:231], v241 offset0:32 offset1:36
	v_add_u32_e32 v241, 0x2000, v240
	ds_read2_b64 v[232:235], v241 offset0:64 offset1:68
	v_add_u32_e32 v241, 0x3000, v240
	ds_read2_b64 v[236:239], v241 offset0:96 offset1:100
	v_add_u32_e32 v205, v151, v141
	s_waitcnt lgkmcnt(7)
	v_mfma_f32_16x16x32_bf16 v[116:119], v[124:127], v[108:111], 0
	v_add_u32_e32 v206, v151, v140
	v_mov_b32_e32 v201, v205
	v_mov_b32_e32 v197, v206
	s_waitcnt lgkmcnt(5)
	v_mfma_f32_16x16x32_bf16 v[120:123], v[132:135], v[108:111], 0
	v_cmp_gt_i32_e64 s[40:41], 1, v201
	v_cmp_gt_i32_e64 s[0:1], 1, v197
	v_add_u32_e32 v153, 0x1400, v153
	v_mfma_f32_16x16x32_bf16 v[116:119], v[128:131], v[112:115], v[116:119]
	s_waitcnt lgkmcnt(4)
	v_mfma_f32_16x16x32_bf16 v[120:123], v[136:139], v[112:115], v[120:123]
	s_nop 5
	v_sub_f32_e32 v116, v116, v174
	v_exp_f32_e32 v191, v116
	v_sub_f32_e32 v116, v120, v174
	v_exp_f32_e32 v192, v116
	v_sub_f32_e32 v116, v117, v174
	v_exp_f32_e32 v194, v116
	v_sub_f32_e32 v116, v121, v174
	v_exp_f32_e32 v196, v116
	v_sub_f32_e32 v116, v118, v174
	v_exp_f32_e32 v198, v116
	v_sub_f32_e32 v116, v122, v174
	v_exp_f32_e32 v200, v116
	v_sub_f32_e32 v116, v119, v174
	v_exp_f32_e32 v202, v116
	v_sub_f32_e32 v116, v123, v174
	v_exp_f32_e32 v204, v116
	v_mfma_f32_16x16x32_bf16 v[116:119], v[124:127], v[68:71], 0
	v_mfma_f32_16x16x32_bf16 v[120:123], v[132:135], v[68:71], 0
	v_mfma_f32_16x16x32_bf16 v[116:119], v[128:131], v[100:103], v[116:119]
	v_mfma_f32_16x16x32_bf16 v[120:123], v[136:139], v[100:103], v[120:123]
	s_nop 6
	v_sub_f32_e32 v116, v116, v174
	v_sub_f32_e32 v120, v120, v174
	v_exp_f32_e32 v116, v116
	v_exp_f32_e32 v193, v120
	v_sub_f32_e32 v120, v121, v174
	v_sub_f32_e32 v117, v117, v174
	v_exp_f32_e32 v195, v120
	v_sub_f32_e32 v120, v122, v174
	v_exp_f32_e32 v117, v117
	v_exp_f32_e32 v199, v120
	v_sub_f32_e32 v120, v123, v174
	v_exp_f32_e32 v203, v120
	v_add_u32_e32 v120, 16, v206
	v_mov_b32_e32 v120, v120
	v_cndmask_b32_e64 v121, 0, v116, s[40:41]
	v_add_u32_e32 v116, 1, v201
	v_cmp_gt_i32_e32 vcc, 1, v120
	v_cndmask_b32_e64 v120, 0, v191, s[0:1]
	v_cndmask_b32_e64 v123, 0, v193, s[0:1]
	v_cmp_gt_i32_e64 s[0:1], 1, v116
	v_add_u32_e32 v191, 1, v197
	v_add_u32_e32 v116, 17, v206
	v_cndmask_b32_e64 v193, 0, v117, s[0:1]
	v_add_u32_e32 v117, 17, v205
	v_sub_f32_e32 v118, v118, v174
	v_cndmask_b32_e32 v122, 0, v192, vcc
	v_cmp_gt_i32_e32 vcc, 1, v191
	v_mov_b32_e32 v117, v117
	v_mov_b32_e32 v116, v116
	v_exp_f32_e32 v118, v118
	v_cndmask_b32_e32 v192, 0, v194, vcc
	v_cmp_gt_i32_e32 vcc, 1, v116
	v_cmp_gt_i32_e64 s[0:1], 1, v117
	v_add_u32_e32 v116, 2, v206
	v_add_u32_e32 v117, 2, v205
	v_mov_b32_e32 v117, v117
	v_mov_b32_e32 v116, v116
	v_sub_f32_e32 v119, v119, v174
	v_cndmask_b32_e64 v195, 0, v195, s[0:1]
	v_cndmask_b32_e32 v194, 0, v196, vcc
	v_cmp_gt_i32_e32 vcc, 1, v116
	v_cmp_gt_i32_e64 s[0:1], 1, v117
	v_add_u32_e32 v116, 18, v206
	v_add_u32_e32 v117, 18, v205
	v_exp_f32_e32 v119, v119
	v_mov_b32_e32 v117, v117
	v_mov_b32_e32 v116, v116
	v_cndmask_b32_e64 v197, 0, v118, s[0:1]
	v_cndmask_b32_e32 v196, 0, v198, vcc
	v_cmp_gt_i32_e32 vcc, 1, v116
	v_cmp_gt_i32_e64 s[0:1], 1, v117
	v_add_u32_e32 v116, 3, v206
	v_add_u32_e32 v117, 3, v205
	v_mov_b32_e32 v117, v117
	v_mov_b32_e32 v116, v116
	v_cndmask_b32_e64 v199, 0, v199, s[0:1]
	v_cndmask_b32_e32 v198, 0, v200, vcc
	v_cmp_gt_i32_e32 vcc, 1, v116
	v_cmp_gt_i32_e64 s[0:1], 1, v117
	v_add_u32_e32 v116, 19, v206
	v_add_u32_e32 v117, 19, v205
	v_cndmask_b32_e64 v201, 0, v119, s[0:1]
	v_cndmask_b32_e32 v200, 0, v202, vcc
	v_mov_b32_e32 v117, v117
	v_mov_b32_e32 v116, v116
	v_cmp_gt_i32_e32 vcc, 1, v116
	v_cmp_gt_i32_e64 s[0:1], 1, v117
	v_pk_add_f32 v[116:117], v[120:121], v[192:193]
	v_pk_add_f32 v[118:119], v[196:197], v[200:201]
	v_cndmask_b32_e64 v203, 0, v203, s[0:1]
	v_cndmask_b32_e32 v202, 0, v204, vcc
	v_pk_add_f32 v[116:117], v[116:117], v[118:119]
	v_pk_add_f32 v[118:119], v[122:123], v[194:195]
	s_nop 0
	v_pk_add_f32 v[116:117], v[116:117], v[118:119]
	v_pk_add_f32 v[118:119], v[198:199], v[202:203]
	s_nop 0
	v_pk_add_f32 v[204:205], v[118:119], v[116:117]
	v_cvt_pk_bf16_f32 v116, v120, v192
	v_cvt_pk_bf16_f32 v118, v122, v194
	v_cvt_pk_bf16_f32 v120, v121, v193
	v_cvt_pk_bf16_f32 v122, v123, v195
	v_mfma_f32_16x16x32_bf16 v[192:195], v[124:127], v[60:63], 0
	v_cvt_pk_bf16_f32 v117, v196, v200
	v_cvt_pk_bf16_f32 v119, v198, v202
	v_cvt_pk_bf16_f32 v121, v197, v201
	v_mfma_f32_16x16x32_bf16 v[124:127], v[124:127], v[52:55], 0
	v_cvt_pk_bf16_f32 v123, v199, v203
	v_pk_add_f32 v[170:171], v[170:171], v[204:205]
	v_mfma_f32_16x16x32_bf16 v[198:201], v[128:131], v[64:67], v[192:195]
	v_mfma_f32_16x16x32_bf16 v[128:131], v[128:131], v[56:59], v[124:127]
	v_mfma_f32_16x16x32_bf16 v[124:127], v[132:135], v[52:55], 0
	s_nop 5
; #define LAS __attribute__((address_space(3)))
; __device__ __forceinline__ void attn_phase(LAS unsigned char* lds, bf16* qkv, const float* qgain, const float* kgain, const float* sink, const float* ropetab, int G, int bid) {
;     ...
;                     const int mbase = msg * (T * 32 + fq * 4 - (whalf * 64 + qi * 16 + fr));
;                     float p0[4], p1[4];
; #pragma unroll
;                     for (int j = 0; j < 4; ++j) {
;                         const float e0 = __builtin_amdgcn_exp2f(s0[j] - Mshift), e1 = __builtin_amdgcn_exp2f(s1[j] - Mshift);
;                         p0[j] = (mbase + msg * j >= 0) ? e0 : 0.f;
;                         p1[j] = (mbase + msg * (16 + j) >= 0) ? e1 : 0.f;
;                     }
;                     lsum[qi] += (p0[0] + p0[1]) + (p0[2] + p0[3]) + (p1[0] + p1[1]) + (p1[2] + p1[3]);
;                     u32x4 w; w.x = cvt_pk_bf16(p0[0], p0[1]); w.y = cvt_pk_bf16(p0[2], p0[3]); w.z = cvt_pk_bf16(p1[0], p1[1]); w.w = cvt_pk_bf16(p1[2], p1[3]);
;                     pb[qi] = __builtin_bit_cast(bf16x8, w);
;                 }
; #pragma unroll
;                 for (int dt = 0; dt < 4; ++dt) {
;                     const LAS unsigned char* vp = Vt + (dt * 16 + fr) * 272 + (T * 32 + fq * 4) * 2;
;                     const u32x2 lo = *(const LAS u32x2*)vp, hi = *(const LAS u32x2*)(vp + 32);
;                     u32x4 w; w.x = lo[0]; w.y = lo[1]; w.z = hi[0]; w.w = hi[1];
;                     const bf16x8 vf = __builtin_bit_cast(bf16x8, w);
; #pragma unroll
;                     for (int qi = 0; qi < 4; ++qi) o[dt][qi] = __builtin_amdgcn_mfma_f32_16x16x32_bf16(vf, pb[qi], o[dt][qi], 0, 0, 0);
;                 }
	v_sub_f32_e32 v191, v198, v174
	v_exp_f32_e32 v198, v191
	v_mfma_f32_16x16x32_bf16 v[192:195], v[132:135], v[60:63], 0
	v_mfma_f32_16x16x32_bf16 v[132:135], v[136:139], v[56:59], v[124:127]
	v_mfma_f32_16x16x32_bf16 v[202:205], v[136:139], v[64:67], v[192:195]
	s_nop 1
	v_sub_f32_e32 v124, v128, v174
	v_exp_f32_e32 v136, v124
	s_nop 2
	v_sub_f32_e32 v124, v132, v174
	v_exp_f32_e32 v132, v124
	v_sub_f32_e32 v124, v129, v174
	v_exp_f32_e32 v129, v124
	v_sub_f32_e32 v124, v133, v174
	v_sub_f32_e32 v191, v202, v174
	v_exp_f32_e32 v128, v124
	v_sub_f32_e32 v124, v130, v174
	v_exp_f32_e32 v197, v191
	v_sub_f32_e32 v191, v199, v174
	v_exp_f32_e32 v127, v124
	v_sub_f32_e32 v124, v134, v174
	v_exp_f32_e32 v196, v191
	v_sub_f32_e32 v191, v203, v174
	v_exp_f32_e32 v126, v124
	v_sub_f32_e32 v124, v131, v174
	v_add_u32_e32 v199, v147, v151
	v_exp_f32_e32 v195, v191
	v_sub_f32_e32 v191, v200, v174
	v_exp_f32_e32 v125, v124
	v_sub_f32_e32 v124, v135, v174
	v_add_u32_e32 v200, v146, v151
	v_add_u32_e32 v134, 16, v199
	v_mov_b32_e32 v135, v199
	v_add_u32_e32 v133, 16, v200
	v_mov_b32_e32 v137, v200
	v_cmp_gt_i32_e64 s[0:1], 1, v135
	v_mov_b32_e32 v134, v134
	v_cmp_gt_i32_e32 vcc, 1, v137
	v_cndmask_b32_e64 v131, 0, v136, s[0:1]
	v_mov_b32_e32 v133, v133
	v_cmp_gt_i32_e64 s[0:1], 1, v134
	v_add_u32_e32 v134, 1, v135
	v_cndmask_b32_e32 v130, 0, v198, vcc
	v_cmp_gt_i32_e32 vcc, 1, v133
	v_cndmask_b32_e64 v133, 0, v132, s[0:1]
	v_add_u32_e32 v135, 1, v137
	v_cmp_gt_i32_e64 s[0:1], 1, v134
	v_cndmask_b32_e32 v132, 0, v197, vcc
	v_cmp_gt_i32_e32 vcc, 1, v135
	v_cndmask_b32_e64 v135, 0, v129, s[0:1]
	v_add_u32_e32 v129, 17, v200
	v_add_u32_e32 v136, 17, v199
	v_mov_b32_e32 v129, v129
	v_cndmask_b32_e32 v134, 0, v196, vcc
	v_mov_b32_e32 v136, v136
	v_cmp_gt_i32_e32 vcc, 1, v129
	v_add_u32_e32 v129, 2, v199
	v_exp_f32_e32 v194, v191
	v_cmp_gt_i32_e64 s[0:1], 1, v136
	v_mov_b32_e32 v129, v129
	v_sub_f32_e32 v191, v204, v174
	v_cndmask_b32_e64 v137, 0, v128, s[0:1]
	v_add_u32_e32 v128, 2, v200
	v_cmp_gt_i32_e64 s[0:1], 1, v129
	v_add_u32_e32 v138, 18, v199
	v_exp_f32_e32 v193, v191
	v_mov_b32_e32 v128, v128
	v_cndmask_b32_e64 v129, 0, v127, s[0:1]
	v_add_u32_e32 v127, 18, v200
	v_mov_b32_e32 v138, v138
	v_sub_f32_e32 v191, v201, v174
	v_cndmask_b32_e32 v136, 0, v195, vcc
	v_cmp_gt_i32_e32 vcc, 1, v128
	v_mov_b32_e32 v127, v127
	v_cmp_gt_i32_e64 s[0:1], 1, v138
	v_exp_f32_e32 v192, v191
	v_cndmask_b32_e32 v128, 0, v194, vcc
	v_cmp_gt_i32_e32 vcc, 1, v127
	v_cndmask_b32_e64 v139, 0, v126, s[0:1]
	v_add_u32_e32 v126, 3, v200
	v_add_u32_e32 v127, 3, v199
	v_sub_f32_e32 v191, v205, v174
	v_exp_f32_e32 v124, v124
	v_mov_b32_e32 v127, v127
	v_mov_b32_e32 v126, v126
	v_exp_f32_e32 v191, v191
	v_cndmask_b32_e32 v138, 0, v193, vcc
	v_cmp_gt_i32_e32 vcc, 1, v126
	v_cmp_gt_i32_e64 s[0:1], 1, v127
	v_add_u32_e32 v126, 19, v199
	v_mov_b32_e32 v126, v126
	v_cndmask_b32_e64 v193, 0, v125, s[0:1]
	v_add_u32_e32 v125, 19, v200
	v_cndmask_b32_e32 v192, 0, v192, vcc
	v_mov_b32_e32 v125, v125
	v_cmp_gt_i32_e64 s[0:1], 1, v126
	v_cmp_gt_i32_e32 vcc, 1, v125
	v_pk_add_f32 v[126:127], v[128:129], v[192:193]
	v_cndmask_b32_e64 v195, 0, v124, s[0:1]
	v_pk_add_f32 v[124:125], v[130:131], v[134:135]
	v_cndmask_b32_e32 v194, 0, v191, vcc
	v_pk_add_f32 v[124:125], v[124:125], v[126:127]
	v_pk_add_f32 v[126:127], v[132:133], v[136:137]
	v_cvt_pk_bf16_f32 v129, v129, v193
	v_pk_add_f32 v[124:125], v[124:125], v[126:127]
	v_pk_add_f32 v[126:127], v[138:139], v[194:195]
	v_add_u32_e32 v151, 32, v151
	v_pk_add_f32 v[196:197], v[126:127], v[124:125]
	v_cvt_pk_bf16_f32 v126, v132, v136
	v_cvt_pk_bf16_f32 v124, v130, v134
	v_cvt_pk_bf16_f32 v125, v128, v192
	v_cvt_pk_bf16_f32 v128, v131, v135
	v_cvt_pk_bf16_f32 v130, v133, v137
	v_cvt_pk_bf16_f32 v127, v138, v194
	v_cvt_pk_bf16_f32 v131, v139, v195
	s_waitcnt lgkmcnt(0)
	v_mfma_f32_16x16x32_bf16 v[104:107], v[224:227], v[116:119], v[104:107]
	s_add_i32 s4, s4, 64
	v_pk_add_f32 v[160:161], v[160:161], v[196:197]
	s_cmpk_eq_i32 s4, 0x100
	v_mfma_f32_16x16x32_bf16 v[48:51], v[224:227], v[120:123], v[48:51]
	v_mfma_f32_16x16x32_bf16 v[32:35], v[224:227], v[124:127], v[32:35]
	v_mfma_f32_16x16x32_bf16 v[16:19], v[224:227], v[128:131], v[16:19]
	v_mfma_f32_16x16x32_bf16 v[96:99], v[228:231], v[116:119], v[96:99]
	v_mfma_f32_16x16x32_bf16 v[40:43], v[228:231], v[120:123], v[40:43]
	v_mfma_f32_16x16x32_bf16 v[24:27], v[228:231], v[124:127], v[24:27]
	v_mfma_f32_16x16x32_bf16 v[4:7], v[228:231], v[128:131], v[4:7]
	v_mfma_f32_16x16x32_bf16 v[88:91], v[232:235], v[116:119], v[88:91]
	v_mfma_f32_16x16x32_bf16 v[44:47], v[232:235], v[120:123], v[44:47]
	v_mfma_f32_16x16x32_bf16 v[28:31], v[232:235], v[124:127], v[28:31]
	v_mfma_f32_16x16x32_bf16 v[12:15], v[232:235], v[128:131], v[12:15]
	v_mfma_f32_16x16x32_bf16 v[80:83], v[236:239], v[116:119], v[80:83]
	v_mfma_f32_16x16x32_bf16 v[36:39], v[236:239], v[120:123], v[36:39]
	v_mfma_f32_16x16x32_bf16 v[20:23], v[236:239], v[124:127], v[20:23]
	v_mfma_f32_16x16x32_bf16 v[8:11], v[236:239], v[128:131], v[8:11]
	s_cbranch_scc0 .LattN_587
	s_branch .Latt_exit
